# speedup vs baseline: 1.0047x; 1.0047x over previous
_Z11mega_kernel1P:
	s_cmpk_lt_u32 s2, 0x100
	s_cbranch_scc1 .LBB0_prio_done
	s_setprio 1
.LBB0_prio_done:
	s_mov_b64 s[36:37], s[0:1]
	s_load_dwordx2 s[0:1], s[0:1], 0xc8
	s_add_u32 s60, s36, 0xd0
	s_addc_u32 s61, s37, 0
	s_mov_b64 s[4:5], 0
	s_waitcnt lgkmcnt(0)
	s_cmp_eq_u64 s[0:1], 0
	s_cbranch_scc1 .LBB0_2
	v_and_b32_e32 v170, 0x3ff, v0
	s_load_dword s34, s[36:37], 0xd0
	s_andn2_b64 vcc, exec, s[4:5]
	s_cbranch_vccz .LBB0_3
	s_branch .LBB0_14
